# MLA QK block: eight K fragments in flight in both bodies and both halves (extra fragments staged in the idle V-fragment registers), counted lgkmcnt waits; amplified A/B about -10 us per attention pass
# speedup vs baseline: 1.0151x; 1.0017x over previous
; __device__ __forceinline__ void finishSM(f32x16& p0, f32x16& p1, float alpha, float& l_reg, bf16x8& pa0, bf16x8& pa1, bf16x8& pa2, bf16x8& pa3) {
; #pragma unroll
;   for (int r = 0; r < 16; ++r) p1[r] = __builtin_amdgcn_exp2f(p1[r]);
;   float ps = 0;
; #pragma unroll
;   for (int r = 0; r < 16; ++r) ps += p0[r];
; #pragma unroll
;   for (int r = 0; r < 16; ++r) ps += p1[r];
;   { auto rr = __builtin_amdgcn_permlane32_swap(__float_as_uint(ps), __float_as_uint(ps), false, false);
;     ps = __uint_as_float(rr[0]) + __uint_as_float(rr[1]); }
;   l_reg = l_reg * alpha + ps;
;     ...
;   PK4(p0, 0, pa0); PK4(p0, 8, pa1); PK4(p1, 0, pa2); PK4(p1, 8, pa3);
;     ...
; }
; template <int DQK> __device__ __forceinline__ void qkt(f32x16& p0, f32x16& p1, const char* Ks, const bf16x8* qr, int r32, int hi) {
;   p0 = f32x16{}; p1 = f32x16{};
; #pragma unroll
;   for (int d0 = 0; d0 < DQK / 16; ++d0) { int cb = (d0 * 16 + hi * 8) * 2;
;     bf16x8 b0 = *reinterpret_cast<const bf16x8*>(Ks + KSWZ(r32, cb));
;     bf16x8 b1 = *reinterpret_cast<const bf16x8*>(Ks + KSWZ(32 + r32, cb));
;     p0 = __builtin_amdgcn_mfma_f32_32x32x16_bf16(b0, qr[d0], p0, 0, 0, 0);
;     p1 = __builtin_amdgcn_mfma_f32_32x32x16_bf16(b1, qr[d0], p1, 0, 0, 0); }
; }
; __device__ __forceinline__ int v_st(int k, int c) { const int kk = (k & ~0xC) | ((k & 4) << 1) | ((k & 8) >> 1); return ((kk >> 3) * 4 + (c >> 5)) * 512 + ((kk & 7) * 32 + (c & 31)) * 2; }
; __device__ __forceinline__ int v_rd_base(int lane) { return ((lane & 3) << 3) | (((lane >> 2) & 3) << 6) | (((lane >> 4) & 1) << 5) | (((lane >> 5) & 1) << 8); }
; template <int OFF> __device__ __forceinline__ s16x4 tr_read(int vb) {
;   s16x4 r; asm volatile("ds_read_b64_tr_b16 %0, %1 offset:%2" : "=&v"(r) : "v"(vb), "i"(OFF) : "memory"); return r;
; }
; template <int D0> __device__ __forceinline__ void pv_one(f32x16& od, int vb, bf16x8 pa0, bf16x8 pa1, bf16x8 pa2, bf16x8 pa3) {
;   const s16x4 l0 = tr_read<v_rd_off(D0, 0, 0)>(vb), h0 = tr_read<v_rd_off(D0, 0, 1)>(vb), l1 = tr_read<v_rd_off(D0, 1, 0)>(vb), h1 = tr_read<v_rd_off(D0, 1, 1)>(vb);
; template <int DQK, int MODE, int ldq, int ldk, int ldv> ...
;     ...
;     SBAR(); qkt<DQK>(pB0, pB1, K_lds + SHM_K, qr, r32, hi);
;     finishSM(pA0, pA1, alA, l_reg, pa0, pa1, pa2, pa3); SBAR();
;     SLOAD(SO, j + 2); SBAR();
;     pv_d0(o, vb0, pa0, pa1, pa2, pa3); BIAS(pB0, pB1, j); partialSM<DQK>(pB0, pB1, m_reg, mnB, alB);
.LBB0_300:
	s_add_i32 s25, s11, -3
	s_cmp_lg_u32 s32, 0
	s_cbranch_scc1 .Lmy_h1B
	ds_read_b128 v[32:35], v148 offset:49152
	ds_read_b128 v[36:39], v148 offset:57344
	ds_read_b128 v[164:167], v152 offset:49152
	ds_read_b128 v[168:171], v152 offset:57344
	ds_read_b128 v[184:187], v151 offset:49152
	ds_read_b128 v[188:191], v151 offset:57344
	ds_read_b128 v[192:195], v149 offset:49152
	ds_read_b128 v[196:199], v149 offset:57344
	s_waitcnt lgkmcnt(7)
	v_mfma_f32_32x32x16_bf16 v[48:63], v[32:35], v[84:87], v[210:225]
	s_waitcnt lgkmcnt(6)
	v_mfma_f32_32x32x16_bf16 v[32:47], v[36:39], v[84:87], v[210:225]
	s_waitcnt lgkmcnt(5)
	v_mfma_f32_32x32x16_bf16 v[48:63], v[164:167], v[80:83], v[48:63]
	s_waitcnt lgkmcnt(4)
	v_mfma_f32_32x32x16_bf16 v[32:47], v[168:171], v[80:83], v[32:47]
	ds_read_b128 v[164:167], v150 offset:49152
	ds_read_b128 v[168:171], v150 offset:57344
	s_waitcnt lgkmcnt(5)
	v_mfma_f32_32x32x16_bf16 v[48:63], v[184:187], v[76:79], v[48:63]
	s_waitcnt lgkmcnt(4)
	v_mfma_f32_32x32x16_bf16 v[32:47], v[188:191], v[76:79], v[32:47]
	ds_read_b128 v[184:187], v153 offset:49152
	ds_read_b128 v[188:191], v153 offset:57344
	s_waitcnt lgkmcnt(5)
	v_mfma_f32_32x32x16_bf16 v[48:63], v[192:195], v[72:75], v[48:63]
	s_waitcnt lgkmcnt(4)
	v_mfma_f32_32x32x16_bf16 v[32:47], v[196:199], v[72:75], v[32:47]
	s_waitcnt lgkmcnt(3)
	v_mfma_f32_32x32x16_bf16 v[48:63], v[164:167], v[68:71], v[48:63]
	s_waitcnt lgkmcnt(2)
	v_mfma_f32_32x32x16_bf16 v[32:47], v[168:171], v[68:71], v[32:47]
	s_waitcnt vmcnt(0)
	ds_write_b128 v146, v[88:91] offset:32768
	ds_write_b128 v147, v[96:99] offset:32768
	ds_write_b128 v145, v[92:95] offset:16384
	s_waitcnt lgkmcnt(4)
	v_mfma_f32_32x32x16_bf16 v[48:63], v[184:187], v[64:67], v[48:63]
	s_waitcnt lgkmcnt(3)
	v_mfma_f32_32x32x16_bf16 v[32:47], v[188:191], v[64:67], v[32:47]
	ds_read_b64_tr_b16 v[184:185], v144 offset:0
	ds_read_b64_tr_b16 v[186:187], v144 offset:0x800
	ds_read_b64_tr_b16 v[188:189], v144 offset:0x1000
	ds_read_b64_tr_b16 v[190:191], v144 offset:0x1800
	ds_read_b64_tr_b16 v[192:193], v144 offset:0x2000
	ds_read_b64_tr_b16 v[194:195], v144 offset:0x2800
	ds_read_b64_tr_b16 v[196:197], v144 offset:0x3000
	ds_read_b64_tr_b16 v[198:199], v144 offset:0x3800
	v_cvt_pk_bf16_f32 v200, v126, v160
	v_cvt_pk_bf16_f32 v201, v127, v161
	v_cvt_pk_bf16_f32 v202, v158, v162
	v_cvt_pk_bf16_f32 v203, v159, v163
	v_cvt_pk_bf16_f32 v226, v118, v121
	v_cvt_pk_bf16_f32 v227, v119, v122
	v_cvt_pk_bf16_f32 v228, v120, v123
	v_cvt_pk_bf16_f32 v229, v124, v125
	v_cvt_pk_bf16_f32 v230, v114, v115
	v_cvt_pk_bf16_f32 v231, v112, v113
	v_cvt_pk_bf16_f32 v232, v108, v109
	v_cvt_pk_bf16_f32 v233, v104, v105
	v_cvt_pk_bf16_f32 v136, v102, v103
	v_cvt_pk_bf16_f32 v137, v110, v111
	v_cvt_pk_bf16_f32 v138, v106, v107
	v_cvt_pk_bf16_f32 v139, v100, v101
	v_add_f32_e32 v155, v126, v160
	v_add_f32_e32 v155, v127, v155
	v_add_f32_e32 v155, v161, v155
	v_add_f32_e32 v155, v158, v155
	v_add_f32_e32 v155, v162, v155
	v_add_f32_e32 v155, v159, v155
	v_add_f32_e32 v155, v163, v155
	v_add_f32_e32 v155, v118, v155
	v_add_f32_e32 v155, v121, v155
	v_add_f32_e32 v155, v119, v155
	v_add_f32_e32 v155, v122, v155
	v_add_f32_e32 v155, v120, v155
	v_add_f32_e32 v155, v123, v155
	v_add_f32_e32 v155, v124, v155
	v_add_f32_e32 v155, v125, v155
	v_add_f32_e32 v155, v114, v155
	v_add_f32_e32 v155, v115, v155
	v_add_f32_e32 v155, v112, v155
	v_add_f32_e32 v155, v113, v155
	v_add_f32_e32 v155, v108, v155
	v_add_f32_e32 v155, v109, v155
	v_add_f32_e32 v155, v104, v155
	v_add_f32_e32 v155, v105, v155
	v_add_f32_e32 v155, v102, v155
	v_add_f32_e32 v155, v103, v155
	v_add_f32_e32 v155, v110, v155
	v_add_f32_e32 v155, v111, v155
	v_add_f32_e32 v155, v106, v155
	v_add_f32_e32 v155, v107, v155
	v_add_f32_e32 v155, v100, v155
	v_add_f32_e32 v155, v101, v155
	s_lshl_b32 s0, s11, 6
	s_cmpk_lt_u32 s25, 0x7e
	s_cselect_b32 s1, s10, s24
	s_add_i32 s1, s1, s0
	s_addk_i32 s1, 0xffc0
	s_mul_i32 s1, s1, 0x300
	s_add_u32 s12, s18, s1
	s_addc_u32 s13, s19, 0
	s_cmpk_lt_u32 s25, 0x7f
	s_cselect_b32 s98, s10, s24
	s_add_i32 s98, s98, s0
	s_addk_i32 s98, 0xff80
	s_lshl_b32 s98, s98, 9
	s_add_u32 s98, s20, s98
	s_addc_u32 s99, s21, 0
	global_load_dwordx4 v[100:103], v134, s[12:13]
	global_load_dwordx4 v[108:111], v135, s[98:99]
	global_load_dwordx4 v[104:107], v238, s[12:13] offset:128
	s_waitcnt lgkmcnt(0)
	s_nop 0
	v_mfma_f32_32x32x16_bf16 v[0:15], v[200:203], v[184:187], v[0:15]
	ds_read_b64_tr_b16 v[184:185], v144 offset:0x200
	ds_read_b64_tr_b16 v[186:187], v144 offset:0xa00
	v_max_f32_e32 v112, v48, v49
	v_max3_f32 v112, v112, v50, v51
	v_max3_f32 v112, v112, v52, v53
	v_max3_f32 v112, v112, v54, v55
	v_max3_f32 v112, v112, v56, v57
	v_mfma_f32_32x32x16_bf16 v[0:15], v[226:229], v[188:191], v[0:15]
	ds_read_b64_tr_b16 v[188:189], v144 offset:0x1200
	ds_read_b64_tr_b16 v[190:191], v144 offset:0x1a00
	v_max3_f32 v112, v112, v58, v59
	v_max3_f32 v112, v112, v60, v61
	v_max3_f32 v112, v112, v62, v63
	v_max3_f32 v112, v112, v32, v33
	v_max3_f32 v112, v112, v34, v35
	v_mfma_f32_32x32x16_bf16 v[0:15], v[230:233], v[192:195], v[0:15]
	ds_read_b64_tr_b16 v[192:193], v144 offset:0x2200
	ds_read_b64_tr_b16 v[194:195], v144 offset:0x2a00
	v_max3_f32 v112, v112, v36, v37
	v_max3_f32 v112, v112, v38, v39
	v_max3_f32 v112, v112, v40, v41
	v_max3_f32 v112, v112, v42, v43
	v_max3_f32 v112, v112, v44, v45
	v_mfma_f32_32x32x16_bf16 v[0:15], v[136:139], v[196:199], v[0:15]
	ds_read_b64_tr_b16 v[196:197], v144 offset:0x3200
	ds_read_b64_tr_b16 v[198:199], v144 offset:0x3a00
	v_max3_f32 v112, v112, v46, v47
	v_cmp_ge_f32_e32 vcc, s80, v112
	s_cmp_eq_u64 vcc, exec
	s_cbranch_scc0 .Lmy_rare_a1
	v_mov_b32_e32 v157, 1.0
	s_mov_b64 vcc, 0

; #define SBAR() __builtin_amdgcn_sched_barrier(0)
; __device__ __forceinline__ void finishSM(f32x16& p0, f32x16& p1, float alpha, float& l_reg, bf16x8& pa0, bf16x8& pa1, bf16x8& pa2, bf16x8& pa3) {
; #pragma unroll
;   for (int r = 0; r < 16; ++r) p1[r] = __builtin_amdgcn_exp2f(p1[r]);
;   float ps = 0;
; #pragma unroll
;   for (int r = 0; r < 16; ++r) ps += p0[r];
; #pragma unroll
;   for (int r = 0; r < 16; ++r) ps += p1[r];
;   { auto rr = __builtin_amdgcn_permlane32_swap(__float_as_uint(ps), __float_as_uint(ps), false, false);
;     ps = __uint_as_float(rr[0]) + __uint_as_float(rr[1]); }
;   l_reg = l_reg * alpha + ps;
;     ...
;   PK4(p0, 0, pa0); PK4(p0, 8, pa1); PK4(p1, 0, pa2); PK4(p1, 8, pa3);
;     ...
; }
; template <int DQK> __device__ __forceinline__ void qkt(f32x16& p0, f32x16& p1, const char* Ks, const bf16x8* qr, int r32, int hi) {
;   p0 = f32x16{}; p1 = f32x16{};
; #pragma unroll
;   for (int d0 = 0; d0 < DQK / 16; ++d0) { int cb = (d0 * 16 + hi * 8) * 2;
;     bf16x8 b0 = *reinterpret_cast<const bf16x8*>(Ks + KSWZ(r32, cb));
;     bf16x8 b1 = *reinterpret_cast<const bf16x8*>(Ks + KSWZ(32 + r32, cb));
;     p0 = __builtin_amdgcn_mfma_f32_32x32x16_bf16(b0, qr[d0], p0, 0, 0, 0);
;     p1 = __builtin_amdgcn_mfma_f32_32x32x16_bf16(b1, qr[d0], p1, 0, 0, 0); }
; }
; __device__ __forceinline__ int v_st(int k, int c) { const int kk = (k & ~0xC) | ((k & 4) << 1) | ((k & 8) >> 1); return ((kk >> 3) * 4 + (c >> 5)) * 512 + ((kk & 7) * 32 + (c & 31)) * 2; }
; __device__ __forceinline__ int v_rd_base(int lane) { return ((lane & 3) << 3) | (((lane >> 2) & 3) << 6) | (((lane >> 4) & 1) << 5) | (((lane >> 5) & 1) << 8); }
; template <int OFF> __device__ __forceinline__ s16x4 tr_read(int vb) {
;   s16x4 r; asm volatile("ds_read_b64_tr_b16 %0, %1 offset:%2" : "=&v"(r) : "v"(vb), "i"(OFF) : "memory"); return r;
; }
; template <int D0> __device__ __forceinline__ void pv_one(f32x16& od, int vb, bf16x8 pa0, bf16x8 pa1, bf16x8 pa2, bf16x8 pa3) {
; template <int DQK, int MODE, int ldq, int ldk, int ldv> ...
;     ...
;     SBAR(); qkt<DQK>(pA0, pA1, K_lds, qr, r32, hi);
;     finishSM(pB0, pB1, alB, l_reg, pa0, pa1, pa2, pa3); SBAR();
;     if (j + 3 < NT) SLOAD(SE, j + 3); SBAR();
;     pv_d0(o, vb0 + (int)SHM_V, pa0, pa1, pa2, pa3); BIAS(pA0, pA1, j + 1); partialSM<DQK>(pA0, pA1, m_reg, mnA, alA);
.LBB0_304:
	s_waitcnt lgkmcnt(0)
	s_barrier
	ds_read_b128 v[32:35], v148 offset:32768
	ds_read_b128 v[36:39], v148 offset:40960
	ds_read_b128 v[176:179], v152 offset:32768
	ds_read_b128 v[180:183], v152 offset:40960
	ds_read_b128 v[184:187], v151 offset:32768
	ds_read_b128 v[188:191], v151 offset:40960
	ds_read_b128 v[192:195], v149 offset:32768
	ds_read_b128 v[196:199], v149 offset:40960
	s_waitcnt lgkmcnt(7)
	v_mfma_f32_32x32x16_bf16 v[48:63], v[32:35], v[84:87], v[210:225]
	s_waitcnt lgkmcnt(6)
	v_mfma_f32_32x32x16_bf16 v[32:47], v[36:39], v[84:87], v[210:225]
	s_waitcnt lgkmcnt(5)
	v_mfma_f32_32x32x16_bf16 v[48:63], v[176:179], v[80:83], v[48:63]
	s_waitcnt lgkmcnt(4)
	v_mfma_f32_32x32x16_bf16 v[32:47], v[180:183], v[80:83], v[32:47]
	ds_read_b128 v[176:179], v150 offset:32768
	ds_read_b128 v[180:183], v150 offset:40960
	s_waitcnt lgkmcnt(5)
	v_mfma_f32_32x32x16_bf16 v[48:63], v[184:187], v[76:79], v[48:63]
	s_waitcnt lgkmcnt(4)
	v_mfma_f32_32x32x16_bf16 v[32:47], v[188:191], v[76:79], v[32:47]
	ds_read_b128 v[184:187], v153 offset:32768
	ds_read_b128 v[188:191], v153 offset:40960
	s_waitcnt lgkmcnt(5)
	v_mfma_f32_32x32x16_bf16 v[48:63], v[192:195], v[72:75], v[48:63]
	s_waitcnt lgkmcnt(4)
	v_mfma_f32_32x32x16_bf16 v[32:47], v[196:199], v[72:75], v[32:47]
	s_waitcnt lgkmcnt(3)
	v_mfma_f32_32x32x16_bf16 v[48:63], v[176:179], v[68:71], v[48:63]
	s_waitcnt lgkmcnt(2)
	v_mfma_f32_32x32x16_bf16 v[32:47], v[180:183], v[68:71], v[32:47]
	s_waitcnt vmcnt(0)
	ds_write_b128 v146, v[100:103] offset:49152
	ds_write_b128 v147, v[104:107] offset:49152
	ds_write_b128 v145, v[108:111]
	s_waitcnt lgkmcnt(4)
	v_mfma_f32_32x32x16_bf16 v[48:63], v[184:187], v[64:67], v[48:63]
	s_waitcnt lgkmcnt(3)
	v_mfma_f32_32x32x16_bf16 v[32:47], v[188:191], v[64:67], v[32:47]
	ds_read_b64_tr_b16 v[184:185], v143 offset:0
	ds_read_b64_tr_b16 v[186:187], v143 offset:0x800
	ds_read_b64_tr_b16 v[188:189], v143 offset:0x1000
	ds_read_b64_tr_b16 v[190:191], v143 offset:0x1800
	ds_read_b64_tr_b16 v[192:193], v143 offset:0x2000
	ds_read_b64_tr_b16 v[194:195], v143 offset:0x2800
	ds_read_b64_tr_b16 v[196:197], v143 offset:0x3000
	ds_read_b64_tr_b16 v[198:199], v143 offset:0x3800
	v_cvt_pk_bf16_f32 v200, v112, v127
	v_cvt_pk_bf16_f32 v201, v113, v126
	v_cvt_pk_bf16_f32 v202, v114, v125
	v_cvt_pk_bf16_f32 v203, v115, v124
	v_cvt_pk_bf16_f32 v226, v116, v123
	v_cvt_pk_bf16_f32 v227, v117, v122
	v_cvt_pk_bf16_f32 v228, v118, v121
	v_cvt_pk_bf16_f32 v229, v119, v120
	v_cvt_pk_bf16_f32 v230, v167, v168
	v_cvt_pk_bf16_f32 v231, v169, v170
	v_cvt_pk_bf16_f32 v232, v171, v172
	v_cvt_pk_bf16_f32 v233, v160, v161
	v_cvt_pk_bf16_f32 v136, v162, v163
	v_cvt_pk_bf16_f32 v137, v164, v165
	v_cvt_pk_bf16_f32 v138, v166, v173
	v_cvt_pk_bf16_f32 v139, v174, v159
	v_add_f32_e32 v156, v112, v127
	v_add_f32_e32 v156, v113, v156
	v_add_f32_e32 v156, v126, v156
	v_add_f32_e32 v156, v114, v156
	v_add_f32_e32 v156, v125, v156
	v_add_f32_e32 v156, v115, v156
	v_add_f32_e32 v156, v124, v156
	v_add_f32_e32 v156, v116, v156
	v_add_f32_e32 v156, v123, v156
	v_add_f32_e32 v156, v117, v156
	v_add_f32_e32 v156, v122, v156
	v_add_f32_e32 v156, v118, v156
	v_add_f32_e32 v156, v121, v156
	v_add_f32_e32 v156, v119, v156
	v_add_f32_e32 v156, v120, v156
	v_add_f32_e32 v156, v167, v156
	v_add_f32_e32 v156, v168, v156
	v_add_f32_e32 v156, v169, v156
	v_add_f32_e32 v156, v170, v156
	v_add_f32_e32 v156, v171, v156
	v_add_f32_e32 v156, v172, v156
	v_add_f32_e32 v156, v160, v156
	v_add_f32_e32 v156, v161, v156
	v_add_f32_e32 v156, v162, v156
	v_add_f32_e32 v156, v163, v156
	v_add_f32_e32 v156, v164, v156
	v_add_f32_e32 v156, v165, v156
	v_add_f32_e32 v156, v166, v156
	v_add_f32_e32 v156, v173, v156
	v_add_f32_e32 v156, v174, v156
	v_add_f32_e32 v156, v159, v156
	s_lshl_b32 s0, s11, 6
	s_cmpk_lt_u32 s25, 0x7e
	s_cselect_b32 s98, s10, s24
	s_add_i32 s98, s98, s0
	s_addk_i32 s98, 0xffc0
	s_lshl_b32 s98, s98, 9
	s_add_u32 s98, s20, s98
	s_addc_u32 s99, s21, 0
	global_load_dwordx4 v[92:95], v135, s[98:99]
	s_cmpk_gt_u32 s25, 0x80
	s_cbranch_scc1 .LBB0_306
	s_cmpk_lt_u32 s25, 0x7d
	s_cselect_b32 s1, s10, s24
	s_add_i32 s1, s1, s0
	s_mul_i32 s1, s1, 0x300
	s_add_u32 s12, s18, s1
	s_addc_u32 s13, s19, 0
	global_load_dwordx4 v[88:91], v134, s[12:13]
	global_load_dwordx4 v[96:99], v238, s[12:13] offset:128

; __device__ __forceinline__ void finishSM(f32x16& p0, f32x16& p1, float alpha, float& l_reg, bf16x8& pa0, bf16x8& pa1, bf16x8& pa2, bf16x8& pa3) {
; #pragma unroll
;   for (int r = 0; r < 16; ++r) p1[r] = __builtin_amdgcn_exp2f(p1[r]);
;   float ps = 0;
; #pragma unroll
;   for (int r = 0; r < 16; ++r) ps += p0[r];
; #pragma unroll
;   for (int r = 0; r < 16; ++r) ps += p1[r];
;   { auto rr = __builtin_amdgcn_permlane32_swap(__float_as_uint(ps), __float_as_uint(ps), false, false);
;     ps = __uint_as_float(rr[0]) + __uint_as_float(rr[1]); }
;   l_reg = l_reg * alpha + ps;
;     ...
;   PK4(p0, 0, pa0); PK4(p0, 8, pa1); PK4(p1, 0, pa2); PK4(p1, 8, pa3);
;     ...
; }
; template <int DQK> __device__ __forceinline__ void qkt(f32x16& p0, f32x16& p1, const char* Ks, const bf16x8* qr, int r32, int hi) {
;   p0 = f32x16{}; p1 = f32x16{};
; #pragma unroll
;   for (int d0 = 0; d0 < DQK / 16; ++d0) { int cb = (d0 * 16 + hi * 8) * 2;
;     bf16x8 b0 = *reinterpret_cast<const bf16x8*>(Ks + KSWZ(r32, cb));
;     bf16x8 b1 = *reinterpret_cast<const bf16x8*>(Ks + KSWZ(32 + r32, cb));
;     p0 = __builtin_amdgcn_mfma_f32_32x32x16_bf16(b0, qr[d0], p0, 0, 0, 0);
;     p1 = __builtin_amdgcn_mfma_f32_32x32x16_bf16(b1, qr[d0], p1, 0, 0, 0); }
; }
; __device__ __forceinline__ int v_st(int k, int c) { const int kk = (k & ~0xC) | ((k & 4) << 1) | ((k & 8) >> 1); return ((kk >> 3) * 4 + (c >> 5)) * 512 + ((kk & 7) * 32 + (c & 31)) * 2; }
; __device__ __forceinline__ int v_rd_base(int lane) { return ((lane & 3) << 3) | (((lane >> 2) & 3) << 6) | (((lane >> 4) & 1) << 5) | (((lane >> 5) & 1) << 8); }
; template <int OFF> __device__ __forceinline__ s16x4 tr_read(int vb) {
;   s16x4 r; asm volatile("ds_read_b64_tr_b16 %0, %1 offset:%2" : "=&v"(r) : "v"(vb), "i"(OFF) : "memory"); return r;
; }
; template <int D0> __device__ __forceinline__ void pv_one(f32x16& od, int vb, bf16x8 pa0, bf16x8 pa1, bf16x8 pa2, bf16x8 pa3) {
;   const s16x4 l0 = tr_read<v_rd_off(D0, 0, 0)>(vb), h0 = tr_read<v_rd_off(D0, 0, 1)>(vb), l1 = tr_read<v_rd_off(D0, 1, 0)>(vb), h1 = tr_read<v_rd_off(D0, 1, 1)>(vb);
; template <int DQK, int MODE, int ldq, int ldk, int ldv> ...
;     ...
;     SBAR(); qkt<DQK>(pB0, pB1, K_lds + SHM_K, qr, r32, hi);
;     finishSM(pA0, pA1, alA, l_reg, pa0, pa1, pa2, pa3); SBAR();
;     SLOAD(SO, j + 2); SBAR();
;     pv_d0(o, vb0, pa0, pa1, pa2, pa3); BIAS(pB0, pB1, j); partialSM<DQK>(pB0, pB1, m_reg, mnB, alB);
.Lmy_h1B:
	s_waitcnt vmcnt(0)
	ds_write_b128 v146, v[88:91] offset:32768
	ds_write_b128 v145, v[92:95] offset:16384
	v_cvt_pk_bf16_f32 v200, v126, v160
	v_cvt_pk_bf16_f32 v201, v127, v161
	v_cvt_pk_bf16_f32 v202, v158, v162
	v_cvt_pk_bf16_f32 v203, v159, v163
	v_cvt_pk_bf16_f32 v226, v118, v121
	v_cvt_pk_bf16_f32 v227, v119, v122
	v_cvt_pk_bf16_f32 v228, v120, v123
	v_cvt_pk_bf16_f32 v229, v124, v125
	v_cvt_pk_bf16_f32 v230, v114, v115
	v_cvt_pk_bf16_f32 v231, v112, v113
	v_cvt_pk_bf16_f32 v232, v108, v109
	v_cvt_pk_bf16_f32 v233, v104, v105
	v_cvt_pk_bf16_f32 v136, v102, v103
	v_cvt_pk_bf16_f32 v137, v110, v111
	v_cvt_pk_bf16_f32 v138, v106, v107
	v_cvt_pk_bf16_f32 v139, v100, v101
	v_add_f32_e32 v155, v126, v160
	v_add_f32_e32 v155, v127, v155
	v_add_f32_e32 v155, v161, v155
	v_add_f32_e32 v155, v158, v155
	v_add_f32_e32 v155, v162, v155
	v_add_f32_e32 v155, v159, v155
	v_add_f32_e32 v155, v163, v155
	v_add_f32_e32 v155, v118, v155
	v_add_f32_e32 v155, v121, v155
	v_add_f32_e32 v155, v119, v155
	v_add_f32_e32 v155, v122, v155
	v_add_f32_e32 v155, v120, v155
	v_add_f32_e32 v155, v123, v155
	v_add_f32_e32 v155, v124, v155
	v_add_f32_e32 v155, v125, v155
	v_add_f32_e32 v155, v114, v155
	v_add_f32_e32 v155, v115, v155
	v_add_f32_e32 v155, v112, v155
	v_add_f32_e32 v155, v113, v155
	v_add_f32_e32 v155, v108, v155
	v_add_f32_e32 v155, v109, v155
	v_add_f32_e32 v155, v104, v155
	v_add_f32_e32 v155, v105, v155
	v_add_f32_e32 v155, v102, v155
	v_add_f32_e32 v155, v103, v155
	v_add_f32_e32 v155, v110, v155
	v_add_f32_e32 v155, v111, v155
	v_add_f32_e32 v155, v106, v155
	v_add_f32_e32 v155, v107, v155
	v_add_f32_e32 v155, v100, v155
	v_add_f32_e32 v155, v101, v155
	s_lshl_b32 s0, s11, 6
	s_cmpk_lt_u32 s25, 0x7e
	s_cselect_b32 s1, s10, s24
	s_add_i32 s1, s1, s0
	s_addk_i32 s1, 0xffc0
	s_mul_i32 s1, s1, 0x300
	s_add_u32 s12, s18, s1
	s_addc_u32 s13, s19, 0
	s_cmpk_lt_u32 s25, 0x7f
	s_cselect_b32 s98, s10, s24
	s_add_i32 s98, s98, s0
	s_addk_i32 s98, 0xff80
	s_lshl_b32 s98, s98, 9
	s_add_u32 s98, s20, s98
	s_addc_u32 s99, s21, 0
	global_load_dwordx4 v[100:103], v134, s[12:13]
	global_load_dwordx4 v[108:111], v135, s[98:99]
	ds_read_b128 v[32:35], v148 offset:49152
	ds_read_b128 v[36:39], v148 offset:57344
	ds_read_b128 v[164:167], v152 offset:49152
	ds_read_b128 v[168:171], v152 offset:57344
	ds_read_b128 v[184:187], v151 offset:49152
	ds_read_b128 v[188:191], v151 offset:57344
	ds_read_b128 v[192:195], v149 offset:49152
	ds_read_b128 v[196:199], v149 offset:57344
	s_waitcnt lgkmcnt(7)
	v_mfma_f32_32x32x16_bf16 v[48:63], v[32:35], v[84:87], v[210:225]
	s_waitcnt lgkmcnt(6)
	v_mfma_f32_32x32x16_bf16 v[32:47], v[36:39], v[84:87], v[210:225]
	s_waitcnt lgkmcnt(5)
	v_mfma_f32_32x32x16_bf16 v[48:63], v[164:167], v[80:83], v[48:63]
	s_waitcnt lgkmcnt(4)
	v_mfma_f32_32x32x16_bf16 v[32:47], v[168:171], v[80:83], v[32:47]
	ds_read_b128 v[164:167], v150 offset:49152
	ds_read_b128 v[168:171], v150 offset:57344
	s_waitcnt lgkmcnt(5)
	v_mfma_f32_32x32x16_bf16 v[48:63], v[184:187], v[76:79], v[48:63]
	s_waitcnt lgkmcnt(4)
	v_mfma_f32_32x32x16_bf16 v[32:47], v[188:191], v[76:79], v[32:47]
	ds_read_b128 v[184:187], v153 offset:49152
	ds_read_b128 v[188:191], v153 offset:57344
	s_waitcnt lgkmcnt(5)
	v_mfma_f32_32x32x16_bf16 v[48:63], v[192:195], v[72:75], v[48:63]
	s_waitcnt lgkmcnt(4)
	v_mfma_f32_32x32x16_bf16 v[32:47], v[196:199], v[72:75], v[32:47]
	s_waitcnt lgkmcnt(3)
	v_mfma_f32_32x32x16_bf16 v[48:63], v[164:167], v[68:71], v[48:63]
	s_waitcnt lgkmcnt(2)
	v_mfma_f32_32x32x16_bf16 v[32:47], v[168:171], v[68:71], v[32:47]
	s_waitcnt lgkmcnt(1)
	v_mfma_f32_32x32x16_bf16 v[48:63], v[184:187], v[64:67], v[48:63]
	s_waitcnt lgkmcnt(0)
	v_mfma_f32_32x32x16_bf16 v[32:47], v[188:191], v[64:67], v[32:47]
	ds_read_b64_tr_b16 v[184:185], v144 offset:0
	ds_read_b64_tr_b16 v[186:187], v144 offset:0x800
	ds_read_b64_tr_b16 v[188:189], v144 offset:0x1000
	ds_read_b64_tr_b16 v[190:191], v144 offset:0x1800
	ds_read_b64_tr_b16 v[192:193], v144 offset:0x2000
	ds_read_b64_tr_b16 v[194:195], v144 offset:0x2800
	ds_read_b64_tr_b16 v[196:197], v144 offset:0x3000
	ds_read_b64_tr_b16 v[198:199], v144 offset:0x3800
	s_waitcnt lgkmcnt(0)
	s_nop 0
	v_mfma_f32_32x32x16_bf16 v[0:15], v[200:203], v[184:187], v[0:15]
	ds_read_b64_tr_b16 v[184:185], v144 offset:0x200
	ds_read_b64_tr_b16 v[186:187], v144 offset:0xa00
	v_mfma_f32_32x32x16_bf16 v[0:15], v[226:229], v[188:191], v[0:15]
	ds_read_b64_tr_b16 v[188:189], v144 offset:0x1200
	ds_read_b64_tr_b16 v[190:191], v144 offset:0x1a00
	v_mfma_f32_32x32x16_bf16 v[0:15], v[230:233], v[192:195], v[0:15]
	ds_read_b64_tr_b16 v[192:193], v144 offset:0x2200
	ds_read_b64_tr_b16 v[194:195], v144 offset:0x2a00
	v_mfma_f32_32x32x16_bf16 v[0:15], v[136:139], v[196:199], v[0:15]
	ds_read_b64_tr_b16 v[196:197], v144 offset:0x3200
	ds_read_b64_tr_b16 v[198:199], v144 offset:0x3a00
	s_waitcnt lgkmcnt(0)
	v_mfma_f32_32x32x16_bf16 v[16:31], v[200:203], v[184:187], v[16:31]
	v_mfma_f32_32x32x16_bf16 v[16:31], v[226:229], v[188:191], v[16:31]
	v_mfma_f32_32x32x16_bf16 v[16:31], v[230:233], v[192:195], v[16:31]
	v_mfma_f32_32x32x16_bf16 v[16:31], v[136:139], v[196:199], v[16:31]
	v_max_f32_e32 v112, v48, v49
	v_max3_f32 v112, v112, v50, v51
	v_max3_f32 v112, v112, v52, v53
	v_max3_f32 v112, v112, v54, v55
	v_max3_f32 v112, v112, v56, v57
	v_max3_f32 v112, v112, v58, v59
	v_max3_f32 v112, v112, v60, v61
	v_max3_f32 v112, v112, v62, v63
	v_max3_f32 v112, v112, v32, v33
	v_max3_f32 v112, v112, v34, v35
	v_max3_f32 v112, v112, v36, v37
	v_max3_f32 v112, v112, v38, v39
	v_max3_f32 v112, v112, v40, v41
	v_max3_f32 v112, v112, v42, v43
	v_max3_f32 v112, v112, v44, v45
	v_max3_f32 v112, v112, v46, v47
	v_cmp_ge_f32_e32 vcc, s80, v112
	s_cmp_eq_u64 vcc, exec
	s_cbranch_scc0 .Lmy_rare_b1
	v_mov_b32_e32 v157, 1.0
	s_mov_b64 vcc, 0

; #define SBAR() __builtin_amdgcn_sched_barrier(0)
; template <int DQK> __device__ __forceinline__ void qkt(f32x16& p0, f32x16& p1, const char* Ks, const bf16x8* qr, int r32, int hi) {
;   p0 = f32x16{}; p1 = f32x16{};
; #pragma unroll
;   for (int d0 = 0; d0 < DQK / 16; ++d0) { int cb = (d0 * 16 + hi * 8) * 2;
;     bf16x8 b0 = *reinterpret_cast<const bf16x8*>(Ks + KSWZ(r32, cb));
;     bf16x8 b1 = *reinterpret_cast<const bf16x8*>(Ks + KSWZ(32 + r32, cb));
;     p0 = __builtin_amdgcn_mfma_f32_32x32x16_bf16(b0, qr[d0], p0, 0, 0, 0);
;     p1 = __builtin_amdgcn_mfma_f32_32x32x16_bf16(b1, qr[d0], p1, 0, 0, 0); }
; }
; __device__ __forceinline__ int v_st(int k, int c) { const int kk = (k & ~0xC) | ((k & 4) << 1) | ((k & 8) >> 1); return ((kk >> 3) * 4 + (c >> 5)) * 512 + ((kk & 7) * 32 + (c & 31)) * 2; }
; __device__ __forceinline__ int v_rd_base(int lane) { return ((lane & 3) << 3) | (((lane >> 2) & 3) << 6) | (((lane >> 4) & 1) << 5) | (((lane >> 5) & 1) << 8); }
; template <int OFF> __device__ __forceinline__ s16x4 tr_read(int vb) {
;   s16x4 r; asm volatile("ds_read_b64_tr_b16 %0, %1 offset:%2" : "=&v"(r) : "v"(vb), "i"(OFF) : "memory"); return r;
; }
; template <int D0> __device__ __forceinline__ void pv_one(f32x16& od, int vb, bf16x8 pa0, bf16x8 pa1, bf16x8 pa2, bf16x8 pa3) {
;   const s16x4 l0 = tr_read<v_rd_off(D0, 0, 0)>(vb), h0 = tr_read<v_rd_off(D0, 0, 1)>(vb), l1 = tr_read<v_rd_off(D0, 1, 0)>(vb), h1 = tr_read<v_rd_off(D0, 1, 1)>(vb);
;   const s16x4 l2 = tr_read<v_rd_off(D0, 2, 0)>(vb), h2 = tr_read<v_rd_off(D0, 2, 1)>(vb), l3 = tr_read<v_rd_off(D0, 3, 0)>(vb), h3 = tr_read<v_rd_off(D0, 3, 1)>(vb);
;   asm volatile("s_waitcnt lgkmcnt(0)" ::: "memory"); SBAR();
;   od = __builtin_amdgcn_mfma_f32_32x32x16_bf16(pa0, PKLH(l0, h0), od, 0, 0, 0);
;   od = __builtin_amdgcn_mfma_f32_32x32x16_bf16(pa1, PKLH(l1, h1), od, 0, 0, 0);
;   od = __builtin_amdgcn_mfma_f32_32x32x16_bf16(pa2, PKLH(l2, h2), od, 0, 0, 0);
;   od = __builtin_amdgcn_mfma_f32_32x32x16_bf16(pa3, PKLH(l3, h3), od, 0, 0, 0);
; }
; template <int DQK, int MODE, int ldq, int ldk, int ldv> ...
;     ...
;     SBAR(); qkt<DQK>(pA0, pA1, K_lds, qr, r32, hi);
;     finishSM(pB0, pB1, alB, l_reg, pa0, pa1, pa2, pa3); SBAR();
;     if (j + 3 < NT) SLOAD(SE, j + 3); SBAR();
;     pv_d0(o, vb0 + (int)SHM_V, pa0, pa1, pa2, pa3); BIAS(pA0, pA1, j + 1); partialSM<DQK>(pA0, pA1, m_reg, mnA, alA);
.Lmy_h2B_306:
	ds_read_b128 v[32:35], v148 offset:32768
	ds_read_b128 v[36:39], v148 offset:40960
	ds_read_b128 v[176:179], v152 offset:32768
	ds_read_b128 v[180:183], v152 offset:40960
	ds_read_b128 v[184:187], v151 offset:32768
	ds_read_b128 v[188:191], v151 offset:40960
	ds_read_b128 v[192:195], v149 offset:32768
	ds_read_b128 v[196:199], v149 offset:40960
	s_waitcnt lgkmcnt(7)
	v_mfma_f32_32x32x16_bf16 v[48:63], v[32:35], v[84:87], v[210:225]
	s_waitcnt lgkmcnt(6)
	v_mfma_f32_32x32x16_bf16 v[32:47], v[36:39], v[84:87], v[210:225]
	s_waitcnt lgkmcnt(5)
	v_mfma_f32_32x32x16_bf16 v[48:63], v[176:179], v[80:83], v[48:63]
	s_waitcnt lgkmcnt(4)
	v_mfma_f32_32x32x16_bf16 v[32:47], v[180:183], v[80:83], v[32:47]
	ds_read_b128 v[176:179], v150 offset:32768
	ds_read_b128 v[180:183], v150 offset:40960
	s_waitcnt lgkmcnt(5)
	v_mfma_f32_32x32x16_bf16 v[48:63], v[184:187], v[76:79], v[48:63]
	s_waitcnt lgkmcnt(4)
	v_mfma_f32_32x32x16_bf16 v[32:47], v[188:191], v[76:79], v[32:47]
	ds_read_b128 v[184:187], v153 offset:32768
	ds_read_b128 v[188:191], v153 offset:40960
	s_waitcnt lgkmcnt(5)
	v_mfma_f32_32x32x16_bf16 v[48:63], v[192:195], v[72:75], v[48:63]
	s_waitcnt lgkmcnt(4)
	v_mfma_f32_32x32x16_bf16 v[32:47], v[196:199], v[72:75], v[32:47]
	s_waitcnt lgkmcnt(3)
	v_mfma_f32_32x32x16_bf16 v[48:63], v[176:179], v[68:71], v[48:63]
	s_waitcnt lgkmcnt(2)
	v_mfma_f32_32x32x16_bf16 v[32:47], v[180:183], v[68:71], v[32:47]
	s_waitcnt lgkmcnt(1)
	v_mfma_f32_32x32x16_bf16 v[48:63], v[184:187], v[64:67], v[48:63]
	s_waitcnt lgkmcnt(0)
	v_mfma_f32_32x32x16_bf16 v[32:47], v[188:191], v[64:67], v[32:47]
	ds_read_b64_tr_b16 v[184:185], v143 offset:0
	ds_read_b64_tr_b16 v[186:187], v143 offset:0x800
	ds_read_b64_tr_b16 v[188:189], v143 offset:0x1000
	ds_read_b64_tr_b16 v[190:191], v143 offset:0x1800
	ds_read_b64_tr_b16 v[192:193], v143 offset:0x2000
	ds_read_b64_tr_b16 v[194:195], v143 offset:0x2800
	ds_read_b64_tr_b16 v[196:197], v143 offset:0x3000
	ds_read_b64_tr_b16 v[198:199], v143 offset:0x3800
	s_waitcnt lgkmcnt(0)
	s_nop 0
	v_mfma_f32_32x32x16_bf16 v[0:15], v[200:203], v[184:187], v[0:15]
	ds_read_b64_tr_b16 v[184:185], v143 offset:0x200
	ds_read_b64_tr_b16 v[186:187], v143 offset:0xa00
	v_mfma_f32_32x32x16_bf16 v[0:15], v[226:229], v[188:191], v[0:15]
	ds_read_b64_tr_b16 v[188:189], v143 offset:0x1200
	ds_read_b64_tr_b16 v[190:191], v143 offset:0x1a00
	v_mfma_f32_32x32x16_bf16 v[0:15], v[230:233], v[192:195], v[0:15]
	ds_read_b64_tr_b16 v[192:193], v143 offset:0x2200
	ds_read_b64_tr_b16 v[194:195], v143 offset:0x2a00
	v_mfma_f32_32x32x16_bf16 v[0:15], v[136:139], v[196:199], v[0:15]
	ds_read_b64_tr_b16 v[196:197], v143 offset:0x3200
	ds_read_b64_tr_b16 v[198:199], v143 offset:0x3a00
	s_waitcnt lgkmcnt(0)
	v_mfma_f32_32x32x16_bf16 v[16:31], v[200:203], v[184:187], v[16:31]
	v_mfma_f32_32x32x16_bf16 v[16:31], v[226:229], v[188:191], v[16:31]
	v_mfma_f32_32x32x16_bf16 v[16:31], v[230:233], v[192:195], v[16:31]
	v_mfma_f32_32x32x16_bf16 v[16:31], v[136:139], v[196:199], v[16:31]
	v_max_f32_e32 v112, v48, v49
	v_max3_f32 v112, v112, v50, v51
	v_max3_f32 v112, v112, v52, v53
	v_max3_f32 v112, v112, v54, v55
	v_max3_f32 v112, v112, v56, v57
	v_max3_f32 v112, v112, v58, v59
	v_max3_f32 v112, v112, v60, v61
	v_max3_f32 v112, v112, v62, v63
	v_max3_f32 v112, v112, v32, v33
	v_max3_f32 v112, v112, v34, v35
	v_max3_f32 v112, v112, v36, v37
	v_max3_f32 v112, v112, v38, v39
	v_max3_f32 v112, v112, v40, v41
	v_max3_f32 v112, v112, v42, v43
	v_max3_f32 v112, v112, v44, v45
	v_max3_f32 v112, v112, v46, v47
	v_cmp_ge_f32_e32 vcc, s80, v112
	s_cmp_eq_u64 vcc, exec
	s_cbranch_scc0 .Lmy_rare_b2
	v_mov_b32_e32 v117, 1.0
	s_mov_b64 vcc, 0
